# attention XCD remap + scan: y stores not waited, DPP cumsum instead of 14 ds_bpermute round trips, tile LDS writes and prefetch loads hoisted to chunk top
# speedup vs baseline: 1.0143x; 1.0041x over previous
; #define LAS __attribute__((address_space(3)))
; DI void scan_phase(PPtr p, int j, ldsp lds, int tid, int wave, int lane) {
;     ...
;             for (int k = 0; k < 4; ++k) { const int id = tid + 512 * k, row = id >> 4, ch = id & 15; const int off = (row * PT + ch * 8) * 2;
;                 *(LAS u32x4*)(lds + O_C + off) = rc[k]; *(LAS u32x4*)(lds + O_B + off) = rb[k]; *(LAS u32x4*)(lds + O_BT + off) = rbt[k]; }
.Lscan_chunk_body:
	v_readlane_b32 s20, v254, 33
	ds_write_b128 v167, v[96:99]
	ds_write_b128 v167, v[80:83] offset:34816
	ds_write_b128 v181, v[88:91]
	ds_write_b128 v181, v[92:95] offset:34816
	v_add_u32_e32 v2, s20, v167
	ds_write_b128 v2, v[84:87]
	v_add_u32_e32 v2, s20, v181
	ds_write_b128 v2, v[100:103]
	ds_write_b128 v182, v[104:107]
	ds_write_b128 v182, v[108:111] offset:34816
	v_add_u32_e32 v2, s20, v182
	ds_write_b128 v2, v[112:115]
	ds_write_b128 v183, v[116:119]
	ds_write_b128 v183, v[120:123] offset:34816
	v_add_u32_e32 v2, s20, v183
	ds_write_b128 v2, v[124:127]
	s_cmp_eq_u32 s18, 31
	s_cbranch_scc1 .Lscan_no_pf
	s_add_i32 s96, s18, 1
	s_lshl_b32 s20, s96, 17
	s_add_u32 s98, s92, s20
	s_addc_u32 s99, s93, 0
	s_add_u32 vcc_lo, s2, s20
	s_addc_u32 vcc_hi, s3, 0
	s_lshl_b32 s96, s96, 8
	s_add_u32 s20, s0, s96
	s_addc_u32 s21, s1, 0
	v_lshl_add_u64 v[2:3], s[98:99], 0, v[148:149]
	global_load_dwordx4 v[96:99], v[2:3], off
	v_lshl_add_u64 v[2:3], vcc, 0, v[148:149]
	global_load_dwordx4 v[80:83], v[2:3], off
	v_lshl_add_u64 v[2:3], v[134:135], 1, s[20:21]
	global_load_dwordx4 v[84:87], v[2:3], off
	v_lshl_add_u64 v[2:3], s[98:99], 0, v[150:151]
	global_load_dwordx4 v[88:91], v[2:3], off
	v_lshl_add_u64 v[2:3], vcc, 0, v[150:151]
	global_load_dwordx4 v[92:95], v[2:3], off
	v_lshl_add_u64 v[2:3], v[138:139], 1, s[20:21]
	global_load_dwordx4 v[100:103], v[2:3], off
	v_lshl_add_u64 v[2:3], s[98:99], 0, v[156:157]
	global_load_dwordx4 v[104:107], v[2:3], off
	v_lshl_add_u64 v[2:3], vcc, 0, v[156:157]
	global_load_dwordx4 v[108:111], v[2:3], off
	v_lshl_add_u64 v[2:3], v[140:141], 1, s[20:21]
	global_load_dwordx4 v[112:115], v[2:3], off
	v_lshl_add_u64 v[2:3], s[98:99], 0, v[158:159]
	global_load_dwordx4 v[116:119], v[2:3], off
	v_lshl_add_u64 v[2:3], vcc, 0, v[158:159]
	global_load_dwordx4 v[120:123], v[2:3], off
	v_lshl_add_u64 v[2:3], v[142:143], 1, s[20:21]
	global_load_dwordx4 v[124:127], v[2:3], off

; DI void scan_phase(PPtr p, int j, ldsp lds, int tid, int wave, int lane) {
;     ...
;                 const float x0 = dr0 + dtb, x1 = dr1 + dtb;
;                 const float d0 = x0 > 20.f ? x0 : log1pf(__expf(x0)), d1 = x1 > 20.f ? x1 : log1pf(__expf(x1));
.LBB0_653:
	s_or_b64 exec, exec, s[98:99]
	v_add_f32_e32 v2, v234, v239
	s_mov_b32 s19, 0x41a00000
	v_cmp_nlt_f32_e32 vcc, s19, v2
	s_and_saveexec_b64 s[98:99], vcc
	s_cbranch_execz .LBB0_655
	v_mul_f32_e32 v2, 0x3fb8aa3b, v2
	v_exp_f32_e32 v32, v2
	s_mov_b32 s19, 0x3f2aaaab
	v_add_f32_e32 v4, 1.0, v32
	v_frexp_mant_f32_e32 v6, v4
	v_cvt_f64_f32_e32 v[2:3], v4
	v_frexp_exp_i32_f64_e32 v2, v[2:3]
	v_cmp_gt_f32_e32 vcc, s19, v6
	v_add_f32_e32 v5, -1.0, v4
	v_sub_f32_e32 v7, v5, v4
	v_subbrev_co_u32_e32 v10, vcc, 0, v2, vcc
	v_sub_u32_e32 v2, 0, v10
	v_sub_f32_e32 v5, v32, v5
	v_add_f32_e32 v7, 1.0, v7
	v_ldexp_f32 v3, v4, v2
	v_add_f32_e32 v5, v5, v7
	v_add_f32_e32 v4, -1.0, v3
	v_add_f32_e32 v6, 1.0, v3
	v_ldexp_f32 v2, v5, v2
	v_add_f32_e32 v5, 1.0, v4
	v_add_f32_e32 v7, -1.0, v6
	v_sub_f32_e32 v5, v3, v5
	v_sub_f32_e32 v3, v3, v7
	v_add_f32_e32 v5, v2, v5
	v_add_f32_e32 v2, v2, v3
	v_add_f32_e32 v11, v6, v2
	v_rcp_f32_e32 v13, v11
	v_sub_f32_e32 v3, v11, v6
	v_sub_f32_e32 v12, v2, v3
	v_add_f32_e32 v3, v4, v5
	v_mul_f32_e32 v15, v3, v13
	v_sub_f32_e32 v2, v3, v4
	v_mul_f32_e32 v4, v11, v15
	v_fma_f32 v6, v15, v11, -v4
	v_fmac_f32_e32 v6, v15, v12
	v_sub_f32_e32 v14, v5, v2
	v_add_f32_e32 v2, v4, v6
	v_sub_f32_e32 v5, v3, v2
	v_pk_add_f32 v[8:9], v[2:3], v[4:5] neg_lo:[0,1] neg_hi:[0,1]
	v_mov_b32_e32 v7, v2
	v_pk_add_f32 v[2:3], v[8:9], v[6:7] neg_lo:[0,1] neg_hi:[0,1]
	s_mov_b32 s19, 0x3f317218
	v_add_f32_e32 v3, v14, v3
	v_add_f32_e32 v2, v2, v3
	v_add_f32_e32 v3, v5, v2
	v_mul_f32_e32 v14, v13, v3
	v_mul_f32_e32 v4, v11, v14
	v_fma_f32 v6, v14, v11, -v4
	v_fmac_f32_e32 v6, v14, v12
	v_sub_f32_e32 v5, v5, v3
	v_add_f32_e32 v11, v2, v5
	v_add_f32_e32 v2, v4, v6
	v_sub_f32_e32 v5, v3, v2
	v_pk_add_f32 v[8:9], v[2:3], v[4:5] neg_lo:[0,1] neg_hi:[0,1]
	v_mov_b32_e32 v7, v2
	v_pk_add_f32 v[2:3], v[8:9], v[6:7] neg_lo:[0,1] neg_hi:[0,1]
	s_nop 0
	v_add_f32_e32 v3, v11, v3
	v_add_f32_e32 v2, v2, v3
	v_add_f32_e32 v3, v15, v14
	v_add_f32_e32 v2, v5, v2
	v_sub_f32_e32 v4, v3, v15
	v_mul_f32_e32 v2, v13, v2
	v_sub_f32_e32 v4, v14, v4
	v_add_f32_e32 v4, v4, v2
	v_add_f32_e32 v6, v3, v4
	v_mul_f32_e32 v7, v6, v6
	v_fmamk_f32 v2, v7, 0x3e9b6dac, v205
	v_fmaak_f32 v155, v7, v2, 0x3f2aaada
	v_cvt_f32_i32_e32 v2, v10
	v_sub_f32_e32 v3, v6, v3
	v_sub_f32_e32 v3, v4, v3
	v_ldexp_f32 v8, v3, 1
	v_mul_f32_e32 v3, v6, v7
	v_ldexp_f32 v5, v6, 1
	v_pk_mul_f32 v[6:7], v[2:3], v[154:155]
	s_nop 0
	v_fma_f32 v4, v2, s19, -v6
	v_fmac_f32_e32 v4, 0xb102e308, v2
	v_pk_add_f32 v[2:3], v[6:7], v[4:5]
	s_mov_b32 s19, 0x7f800000
	v_sub_f32_e32 v5, v3, v5
	v_sub_f32_e32 v5, v7, v5
	v_add_f32_e32 v9, v8, v5
	v_mov_b32_e32 v8, v6
	v_pk_add_f32 v[6:7], v[2:3], v[6:7] neg_lo:[0,1] neg_hi:[0,1]
	v_pk_add_f32 v[10:11], v[2:3], v[8:9]
	v_mov_b32_e32 v5, v2
	v_mov_b32_e32 v7, v11
	v_pk_add_f32 v[12:13], v[4:5], v[6:7] neg_lo:[0,1] neg_hi:[0,1]
	v_pk_add_f32 v[4:5], v[4:5], v[6:7]
	v_mov_b32_e32 v8, v9
	v_pk_add_f32 v[6:7], v[4:5], v[2:3] op_sel:[1,0] op_sel_hi:[0,1] neg_lo:[0,1] neg_hi:[0,1]
	v_pk_add_f32 v[14:15], v[10:11], v[6:7] op_sel_hi:[1,0] neg_lo:[0,1] neg_hi:[0,1]
	v_mov_b32_e32 v10, v11
	v_mov_b32_e32 v11, v5
	v_pk_mov_b32 v[6:7], v[2:3], v[6:7] op_sel:[1,0]
	v_mov_b32_e32 v9, v2
	v_pk_add_f32 v[6:7], v[10:11], v[6:7] neg_lo:[0,1] neg_hi:[0,1]
	v_mov_b32_e32 v14, v12
	v_pk_add_f32 v[2:3], v[8:9], v[6:7] neg_lo:[0,1] neg_hi:[0,1]
	v_mov_b32_e32 v13, v5
	v_pk_add_f32 v[6:7], v[14:15], v[2:3]
	v_cmp_neq_f32_e32 vcc, s19, v32
	v_pk_add_f32 v[8:9], v[6:7], v[6:7] op_sel:[0,1] op_sel_hi:[1,0]
	s_mov_b32 s19, 0x33800000
	v_pk_add_f32 v[4:5], v[4:5], v[8:9] op_sel:[1,0] op_sel_hi:[0,1]
	v_mov_b32_e32 v7, v4
	v_pk_add_f32 v[10:11], v[6:7], v[12:13] neg_lo:[0,1] neg_hi:[0,1]
	v_mov_b32_e32 v3, v8
	v_sub_f32_e32 v5, v6, v10
	v_pk_add_f32 v[2:3], v[2:3], v[10:11] neg_lo:[0,1] neg_hi:[0,1]
	v_sub_f32_e32 v5, v12, v5
	v_add_f32_e32 v2, v2, v5
	v_add_f32_e32 v2, v2, v3
	v_add_f32_e32 v2, v4, v2
	v_cndmask_b32_e32 v2, v215, v2, vcc
	v_cmp_ngt_f32_e32 vcc, -1.0, v32
	s_nop 1
	v_cndmask_b32_e32 v2, v216, v2, vcc
	v_cmp_neq_f32_e32 vcc, -1.0, v32
	s_nop 1
	v_cndmask_b32_e32 v2, v217, v2, vcc
	v_cmp_lt_f32_e64 vcc, |v32|, s19
	s_nop 1
	v_cndmask_b32_e32 v2, v2, v32, vcc
; DI void scan_phase(PPtr p, int j, ldsp lds, int tid, int wave, int lane) {
;     ...
;                 float v0 = d0 * A * 1.4426950408889634f, v1 = d1 * A * 1.4426950408889634f;
; #pragma unroll
;                 for (int off = 1; off < 64; off <<= 1) { const float n0 = __shfl_up(v0, off), n1 = __shfl_up(v1, off); if (lane >= off) { v0 += n0; v1 += n1; } }
;                 v1 += __shfl(v0, 63);
;                 s_dt[lane] = d0; s_dt[lane + 64] = d1; s_ac[lane] = v0; s_ac[lane + 64] = v1;
.LBB0_655:
	s_or_b64 exec, exec, s[98:99]
	v_mul_f32_e64 v3, v0, -v236
	v_mul_f32_e32 v3, 0x3fb8aa3b, v3
	v_mul_f32_e64 v4, v2, -v236
	v_mul_f32_e32 v4, 0x3fb8aa3b, v4
	ds_write2st64_b32 v166, v0, v2 offset1:1
	v_readlane_b32 s19, v254, 33
	v_add_u32_e32 v36, 0, v167
	v_add_f32_dpp v3, v3, v3 row_shr:1 row_mask:0xf bank_mask:0xf bound_ctrl:0
	v_add_f32_dpp v4, v4, v4 row_shr:1 row_mask:0xf bank_mask:0xf bound_ctrl:0
	s_nop 1
	v_add_f32_dpp v3, v3, v3 row_shr:2 row_mask:0xf bank_mask:0xf bound_ctrl:0
	v_add_f32_dpp v4, v4, v4 row_shr:2 row_mask:0xf bank_mask:0xf bound_ctrl:0
	s_nop 1
	v_add_f32_dpp v3, v3, v3 row_shr:4 row_mask:0xf bank_mask:0xf bound_ctrl:0
	v_add_f32_dpp v4, v4, v4 row_shr:4 row_mask:0xf bank_mask:0xf bound_ctrl:0
	s_nop 1
	v_add_f32_dpp v3, v3, v3 row_shr:8 row_mask:0xf bank_mask:0xf bound_ctrl:0
	v_add_f32_dpp v4, v4, v4 row_shr:8 row_mask:0xf bank_mask:0xf bound_ctrl:0
	s_nop 1
	v_add_f32_dpp v3, v3, v3 row_bcast:15 row_mask:0xa bank_mask:0xf
	v_add_f32_dpp v4, v4, v4 row_bcast:15 row_mask:0xa bank_mask:0xf
	s_nop 1
	v_add_f32_dpp v3, v3, v3 row_bcast:31 row_mask:0xc bank_mask:0xf
	v_add_f32_dpp v4, v4, v4 row_bcast:31 row_mask:0xc bank_mask:0xf
	s_nop 1
	v_readlane_b32 s20, v3, 63
	v_add_u32_e32 v5, s19, v167
	v_add_u32_e32 v6, 0, v181
	v_add_u32_e32 v2, s33, v165
	v_add_f32_e32 v0, s20, v4
	ds_write2st64_b32 v2, v3, v0 offset1:1
	v_mov_b32_e32 v0, s33
	ds_read_b32 v0, v0 offset:508
	ds_read_b128 v[2:5], v169
	ds_read_b128 v[6:9], v168
	ds_read_b128 v[10:13], v168 offset:16
	ds_read_b128 v[32:35], v169 offset:16
	s_add_i32 s19, s18, 1
	s_waitcnt lgkmcnt(3)
	v_sub_f32_e32 v2, v0, v2
	v_exp_f32_e32 v14, v2
	v_sub_f32_e32 v2, v0, v3
	v_exp_f32_e32 v15, v2
	v_lshlrev_b32_e32 v2, 16, v128
	v_and_b32_e32 v3, 0xffff0000, v128
	s_waitcnt lgkmcnt(2)
	v_pk_mul_f32 v[6:7], v[6:7], v[2:3]
	v_sub_f32_e32 v3, v0, v4
	v_exp_f32_e32 v4, v3
	v_sub_f32_e32 v3, v0, v5
	v_exp_f32_e32 v5, v3
	v_cvt_pk_bf16_f32 v2, v6, v7
	v_pk_mul_f32 v[6:7], v[6:7], v[14:15]
	v_lshlrev_b32_e32 v14, 16, v129
	v_and_b32_e32 v15, 0xffff0000, v129
	v_pk_mul_f32 v[8:9], v[8:9], v[14:15]
	v_cvt_pk_bf16_f32 v6, v6, v7
	v_pk_mul_f32 v[4:5], v[8:9], v[4:5]
	v_cvt_pk_bf16_f32 v3, v8, v9
	v_cvt_pk_bf16_f32 v7, v4, v5
	s_waitcnt lgkmcnt(0)
	v_sub_f32_e32 v4, v0, v32
	v_exp_f32_e32 v8, v4
	v_sub_f32_e32 v4, v0, v33
	v_exp_f32_e32 v9, v4
	v_lshlrev_b32_e32 v4, 16, v130
	v_and_b32_e32 v5, 0xffff0000, v130
	v_pk_mul_f32 v[10:11], v[10:11], v[4:5]
	v_sub_f32_e32 v5, v0, v34
	v_sub_f32_e32 v0, v0, v35
	v_cvt_pk_bf16_f32 v4, v10, v11
	v_pk_mul_f32 v[8:9], v[10:11], v[8:9]
	v_exp_f32_e32 v10, v5
	v_exp_f32_e32 v11, v0
	v_lshlrev_b32_e32 v14, 16, v131
	v_and_b32_e32 v15, 0xffff0000, v131
	v_pk_mul_f32 v[12:13], v[12:13], v[14:15]
	v_add_u32_e32 v0, 0x19800, v36
	v_cvt_pk_bf16_f32 v5, v12, v13
	v_pk_mul_f32 v[10:11], v[12:13], v[10:11]
	v_cvt_pk_bf16_f32 v8, v8, v9
	v_cvt_pk_bf16_f32 v9, v10, v11
	ds_write_b128 v0, v[2:5]
	v_add_u32_e32 v0, 0x1ba00, v36
	s_cmp_eq_u32 s18, 31
	ds_write_b128 v0, v[6:9]
	s_cbranch_scc1 .LBB0_657
	s_lshl_b32 s96, s19, 8
	v_lshl_or_b32 v0, s19, 7, v137
	v_lshl_add_u64 v[2:3], v[160:161], 0, s[96:97]
	v_lshlrev_b32_e32 v0, 5, v0
	global_load_dwordx4 v[128:131], v[2:3], off
	v_lshl_add_u64 v[2:3], v[0:1], 2, s[94:95]
	global_load_dword v238, v[2:3], off
	v_add_co_u32_e32 v2, vcc, 0x2000, v2
	s_mov_b32 s23, s22
	s_nop 0
	v_addc_co_u32_e32 v3, vcc, 0, v3, vcc
	global_load_dword v239, v[2:3], off
